# odd attention: K/V ring prefetch distance 2, workgroup barrier only on even steps (waves of a SIMD may drift inside a step pair)
# speedup vs baseline: 1.0173x; 1.0021x over previous
; DI float bf2f(short s) { return __uint_as_float(((unsigned)(unsigned short)s) << 16); }
; DI float q_norm(bf16x8 q0, bf16x8 q1) {
;     float ss = 0.f;
; #pragma unroll
;     for (int e = 0; e < 8; ++e) { const float a = bf2f(q0[e]), b = bf2f(q1[e]); ss += a * a + b * b; }
;     ss += __shfl_xor(ss, 16); ss += __shfl_xor(ss, 32);
;     return sqrtf(ss);
; }
; DI void attn_odd_lds(Frame& F, const float* gk  , const float* gq  , bool with_ctx) {
;     ...
; #pragma unroll
;         for (int h = 0; h < 4; ++h) { q[h][0] = *(const bf16x8*)(qp + h * 64); q[h][1] = *(const bf16x8*)(qp + h * 64 + 32); { int gl_ = g; asm volatile("" : "+v"(gl_)); if (isc) q_prep<false>(q[h][0], q[h][1], gq, gl_, nullptr, 0); else q_prep<true>(q[h][0], q[h][1], gq, gl_, WSP(float, WS_ROPE), tq + F.wave * 16 + l16); } mx[h] = q_norm(q[h][0], q[h][1]) * kn; ls[h] = 0.f;
.LBB0_257:
	v_cvt_pk_bf16_f32 v46, v30, v31
	v_cvt_pk_bf16_f32 v42, v50, v51
	v_cvt_pk_bf16_f32 v49, v28, v29
	v_lshlrev_b32_e32 v29, 16, v46
	s_waitcnt lgkmcnt(0)
	v_add_f32_e32 v26, v64, v65
	v_lshlrev_b32_e32 v28, 16, v42
	v_mul_f32_e32 v29, v29, v29
	v_and_b32_e32 v30, 0xffff0000, v46
	v_mul_f32_e32 v27, 0x4f800000, v26
	v_cmp_gt_f32_e32 vcc, s48, v26
	v_fmac_f32_e32 v29, v28, v28
	v_and_b32_e32 v28, 0xffff0000, v42
	v_mul_f32_e32 v30, v30, v30
	v_cndmask_b32_e32 v27, v26, v27, vcc
	v_cvt_pk_bf16_f32 v47, v32, v33
	v_fmac_f32_e32 v30, v28, v28
	v_sqrt_f32_e32 v34, v27
	v_cvt_pk_bf16_f32 v43, v54, v55
	v_add_f32_e32 v28, v29, v30
	v_lshlrev_b32_e32 v30, 16, v47
	v_lshlrev_b32_e32 v29, 16, v43
	v_mul_f32_e32 v30, v30, v30
	v_fmac_f32_e32 v30, v29, v29
	v_add_f32_e32 v28, v30, v28
	v_and_b32_e32 v30, 0xffff0000, v47
	v_add_u32_e32 v35, -1, v34
	v_and_b32_e32 v29, 0xffff0000, v43
	v_mul_f32_e32 v30, v30, v30
	v_fma_f32 v36, -v35, v34, v27
	v_cvt_pk_bf16_f32 v48, v58, v59
	v_fmac_f32_e32 v30, v29, v29
	v_cmp_ge_f32_e64 s[4:5], 0, v36
	v_add_u32_e32 v36, 1, v34
	v_cvt_pk_bf16_f32 v44, v52, v53
	v_add_f32_e32 v28, v30, v28
	v_lshlrev_b32_e32 v30, 16, v48
	v_cndmask_b32_e64 v35, v34, v35, s[4:5]
	v_fma_f32 v34, -v36, v34, v27
	v_lshlrev_b32_e32 v29, 16, v44
	v_mul_f32_e32 v30, v30, v30
	v_cmp_lt_f32_e64 s[4:5], 0, v34
	v_fmac_f32_e32 v30, v29, v29
	v_add_f32_e32 v28, v30, v28
	v_cndmask_b32_e64 v34, v35, v36, s[4:5]
	v_add_f32_e32 v36, v62, v63
	v_and_b32_e32 v30, 0xffff0000, v48
	v_mul_f32_e32 v37, 0x4f800000, v36
	v_cmp_gt_f32_e64 s[4:5], s48, v36
	v_and_b32_e32 v29, 0xffff0000, v44
	v_mul_f32_e32 v30, v30, v30
	v_cndmask_b32_e64 v36, v36, v37, s[4:5]
	v_fmac_f32_e32 v30, v29, v29
	v_sqrt_f32_e32 v37, v36
	v_cvt_pk_bf16_f32 v45, v56, v57
	v_add_f32_e32 v28, v30, v28
	v_lshlrev_b32_e32 v30, 16, v49
	v_lshlrev_b32_e32 v29, 16, v45
	v_mul_f32_e32 v30, v30, v30
	v_mul_f32_e32 v35, 0x37800000, v34
	v_fmac_f32_e32 v30, v29, v29
	v_cndmask_b32_e32 v34, v34, v35, vcc
	v_cmp_class_f32_e32 vcc, v27, v187
	v_add_f32_e32 v28, v30, v28
	v_and_b32_e32 v30, 0xffff0000, v49
	v_cndmask_b32_e32 v27, v34, v27, vcc
	v_add_u32_e32 v34, -1, v37
	v_and_b32_e32 v29, 0xffff0000, v45
	v_mul_f32_e32 v30, v30, v30
	v_fma_f32 v35, -v34, v37, v36
	v_fmac_f32_e32 v30, v29, v29
	v_cmp_ge_f32_e32 vcc, 0, v35
	v_add_u32_e32 v35, 1, v37
	v_add_f32_e32 v28, v30, v28
	v_cndmask_b32_e32 v34, v37, v34, vcc
	v_fma_f32 v37, -v35, v37, v36
	ds_bpermute_b32 v29, v120, v28
	v_cmp_lt_f32_e32 vcc, 0, v37
	v_add_f32_e32 v37, v60, v61
	v_mul_f32_e32 v38, 0x4f800000, v37
	v_cndmask_b32_e32 v34, v34, v35, vcc
	v_cmp_gt_f32_e32 vcc, s48, v37
	s_waitcnt lgkmcnt(0)
	v_add_f32_e32 v28, v28, v29
	ds_bpermute_b32 v29, v121, v28
	v_cndmask_b32_e32 v37, v37, v38, vcc
	v_sqrt_f32_e32 v38, v37
	v_mul_f32_e32 v35, 0x37800000, v34
	v_cndmask_b32_e64 v34, v34, v35, s[4:5]
	v_cmp_class_f32_e64 s[4:5], v36, v187
	v_add_u32_e32 v35, -1, v38
	v_fma_f32 v30, -v35, v38, v37
	v_add_u32_e32 v31, 1, v38
	v_cndmask_b32_e64 v34, v34, v36, s[4:5]
	v_cmp_ge_f32_e64 s[4:5], 0, v30
	v_fma_f32 v32, -v31, v38, v37
	s_waitcnt lgkmcnt(0)
; #define LAS __attribute__((address_space(3)))
; #define LDS_V(sv, db, cb) lds_v((sv), 2 * (db) * AT_GRP + (cb) * 128)
; #define AT_WAIT_BAR(N) asm volatile("s_waitcnt vmcnt(" #N ") lgkmcnt(0)\n\ts_barrier" ::: "memory")
; DI void attn_odd_lds(Frame& F, const float* gk  , const float* gq  , bool with_ctx) {
;     ...
;         for (int h = 0; h < 4; ++h) { q[h][0] = *(const bf16x8*)(qp + h * 64); q[h][1] = *(const bf16x8*)(qp + h * 64 + 32); { int gl_ = g; asm volatile("" : "+v"(gl_)); if (isc) q_prep<false>(q[h][0], q[h][1], gq, gl_, nullptr, 0); else q_prep<true>(q[h][0], q[h][1], gq, gl_, WSP(float, WS_ROPE), tq + F.wave * 16 + l16); } mx[h] = q_norm(q[h][0], q[h][1]) * kn; ls[h] = 0.f;
; #pragma unroll
;             for (int d = 0; d < 4; ++d) o[h][d] = (f32x4){0.f, 0.f, 0.f, 0.f}; }
;         const bf16_t* Kl = P + (size_t)(b * SEQ) * kp + 512 + kvh * 64; const bf16_t* Vl = VT + (size_t)(kvh * 64) * TT + b * SEQ;
;         const bf16_t* Kc = P + (size_t)(TL + b * CTXL) * kp + 512 + kvh * 64; const bf16_t* Vc = VT + (size_t)(kvh * 64) * TT + TL + b * CTXL;
;         const int n = nlat + 4;
;     ...
;         AT_ISSUE(0); AT_ISSUE(1); AT_ISSUE(2);
; #pragma unroll 1
;         for (int s = 0; s < n; ++s) {
;             if (s + 2 < n) AT_WAIT_BAR(4); else if (s + 1 < n) AT_WAIT_BAR(2); else AT_WAIT_BAR(0);
;             if (s + 3 < n) AT_ISSUE(s + 3);
;             const LAS unsigned char* sk = F.lds + (s & 3) * AT_SLOT + bk; const LAS unsigned char* sv = F.lds + (s & 3) * AT_SLOT + bv;
; #pragma unroll
;             for (int hf = 0; hf < 2; ++hf) {
;                 const bf16x8 k00 = LDS_K(sk, hf * 32, 0, 0), k01 = LDS_K(sk, hf * 32, 0, 1), k10 = LDS_K(sk, hf * 32, 1, 0), k11 = LDS_K(sk, hf * 32, 1, 1);
;                 const bf16x8 v0 = LDS_V(sv, 0, hf * 4), v1 = LDS_V(sv, 1, hf * 4), v2 = LDS_V(sv, 2, hf * 4), v3 = LDS_V(sv, 3, hf * 4);
	v_add_f32_e32 v28, v28, v29
	v_cndmask_b32_e64 v30, v38, v35, s[4:5]
	v_cmp_lt_f32_e64 s[4:5], 0, v32
	v_mul_f32_e32 v29, 0x4f800000, v28
	s_ashr_i32 s73, s72, 31
	v_cndmask_b32_e64 v30, v30, v31, s[4:5]
	v_cmp_gt_f32_e64 s[4:5], s48, v28
	v_mul_f32_e32 v31, 0x37800000, v30
	v_cndmask_b32_e32 v30, v30, v31, vcc
	v_cndmask_b32_e64 v28, v28, v29, s[4:5]
	v_sqrt_f32_e32 v29, v28
	v_cmp_class_f32_e32 vcc, v37, v187
	v_mov_b32_e32 v26, 0
	v_mul_f32_e64 v133, v126, -v34
	v_mov_b32_e32 v232, v133
	v_mov_b32_e32 v233, v133
	v_mov_b32_e32 v234, v133
	v_mov_b32_e32 v235, v133
	v_add_u32_e32 v31, -1, v29
	v_fma_f32 v32, -v31, v29, v28
	v_cndmask_b32_e32 v30, v30, v37, vcc
	v_cmp_ge_f32_e32 vcc, 0, v32
	v_add_u32_e32 v32, 1, v29
	v_mul_f32_e64 v132, v126, -v30
	v_mov_b32_e32 v228, v132
	v_mov_b32_e32 v229, v132
	v_mov_b32_e32 v230, v132
	v_mov_b32_e32 v231, v132
	v_cndmask_b32_e32 v31, v29, v31, vcc
	v_fma_f32 v29, -v32, v29, v28
	v_cmp_lt_f32_e32 vcc, 0, v29
	v_mul_f32_e64 v134, v126, -v27
	v_mov_b32_e32 v236, v134
	v_mov_b32_e32 v237, v134
	v_mov_b32_e32 v238, v134
	v_mov_b32_e32 v239, v134
	v_mov_b32_e32 v27, v26
	v_cndmask_b32_e32 v29, v31, v32, vcc
	v_mul_f32_e32 v31, 0x37800000, v29
	v_cndmask_b32_e64 v29, v29, v31, s[4:5]
	s_mul_i32 s5, s72, 0xe00
	s_mul_hi_i32 s4, s72, 0xe00
	s_add_u32 s5, s62, s5
	s_addc_u32 s4, s63, s4
	s_add_u32 s12, s5, 0x400
	s_addc_u32 s13, s4, 0
	s_lshl_b32 s20, s11, 7
	s_add_u32 s5, s5, s20
	s_addc_u32 s4, s4, 0
	s_add_u32 s19, s5, 0x400
	s_addc_u32 s22, s4, 0
	s_mul_i32 s11, s11, 0x880000
	s_add_u32 s29, s42, s11
	s_addc_u32 s30, s43, 0
	s_lshl_b64 s[4:5], s[72:73], 1
	s_add_u32 s11, s29, s4
	s_addc_u32 s26, s30, s5
	s_mul_hi_i32 s4, s10, 0xe00
	s_mulk_i32 s10, 0xe00
	s_add_u32 s5, s62, s10
	s_addc_u32 s4, s63, s4
	s_add_u32 s34, s5, 0x400
	s_addc_u32 s39, s4, 0
	s_add_u32 s5, s5, s20
	s_addc_u32 s4, s4, 0
	s_add_u32 s10, s5, 0x400
	s_addc_u32 s28, s4, 0
	s_ashr_i32 s71, s70, 31
	s_lshl_b64 s[4:5], s[70:71], 1
	s_add_u32 s4, s29, s4
	s_addc_u32 s5, s30, s5
	s_add_u32 s30, s4, 0x20000
	s_addc_u32 s31, s5, 0
	s_or_b32 s33, s18, 4
	s_and_b64 s[4:5], s[68:69], exec
	s_cselect_b32 s4, s19, s10
	s_cselect_b32 s5, s22, s28
	s_cselect_b32 s37, s26, s31
	s_cselect_b32 s36, s11, s30
	s_mov_b32 s29, m0
	s_mov_b32 m0, s80
	s_nop 0
	global_load_lds_dwordx4 v124, s[4:5]
	s_mov_b32 m0, s29
	s_add_i32 s4, s80, 0x2400
	s_mov_b32 s5, m0
	s_mov_b32 m0, s4
	s_nop 0
	global_load_lds_dwordx4 v125, s[36:37]
	s_mov_b32 m0, s5
	s_and_b64 s[4:5], s[68:69], exec
	s_cselect_b32 s5, s12, s34
	s_cselect_b32 s4, s13, s39
	s_add_u32 s12, s5, s20
	s_addc_u32 s13, s4, 0
	s_add_u32 s4, s12, 0x38000
	s_addc_u32 s5, s13, 0
	s_add_u32 s40, s36, 0x80
	s_addc_u32 s41, s37, 0
	s_mov_b32 s20, m0
	s_mov_b32 m0, s81
	s_nop 0
	global_load_lds_dwordx4 v124, s[4:5]
	s_mov_b32 m0, s20
	s_add_i32 s4, s81, 0x2400
	s_mov_b32 s5, m0
	s_mov_b32 m0, s4
	s_nop 0
	global_load_lds_dwordx4 v125, s[40:41]
	s_mov_b32 m0, s5
	s_add_u32 s4, s12, 0x70000
	s_addc_u32 s5, s13, 0
	s_add_u32 s36, s36, 0x100
	s_mov_b32 s12, m0
	s_mov_b32 m0, s82
	s_nop 0
	s_mov_b32 m0, s12
	v_cmp_class_f32_e32 vcc, v28, v187
	s_addc_u32 s37, s37, 0
	s_add_i32 s4, s82, 0x2400
	s_mov_b32 s5, m0
	s_mov_b32 m0, s4
	s_nop 0
	s_mov_b32 m0, s5
	v_cndmask_b32_e32 v28, v29, v28, vcc
	s_or_b32 s34, s18, 2
	s_or_b32 s36, s18, 3
	v_mul_f32_e64 v135, v126, -v28
	v_mov_b32_e32 v240, v135
	v_mov_b32_e32 v241, v135
	v_mov_b32_e32 v242, v135
	v_mov_b32_e32 v243, v135
	s_add_i32 s37, s18, 4
	s_movk_i32 s39, 0x80
	v_mov_b32_e32 v28, v26
	v_mov_b32_e32 v29, v26
	v_mov_b32_e32 v30, v26
	v_mov_b32_e32 v31, v26
	v_mov_b32_e32 v32, v26
	v_mov_b32_e32 v33, v26
	v_mov_b32_e32 v34, v26
	v_mov_b32_e32 v35, v26
	v_mov_b32_e32 v36, v26
	v_mov_b32_e32 v37, v26
	v_mov_b32_e32 v38, v26
	v_mov_b32_e32 v39, v26
	v_mov_b32_e32 v40, v26
	v_mov_b32_e32 v41, v26
	v_mov_b32_e32 v50, v26
	v_mov_b32_e32 v51, v26
	v_mov_b32_e32 v52, v26
	v_mov_b32_e32 v53, v26
	v_mov_b32_e32 v54, v26
	v_mov_b32_e32 v55, v26
	v_mov_b32_e32 v56, v26
	v_mov_b32_e32 v57, v26
	v_mov_b32_e32 v58, v26
	v_mov_b32_e32 v59, v26
	v_mov_b32_e32 v60, v26
	v_mov_b32_e32 v61, v26
	v_mov_b32_e32 v62, v26
	v_mov_b32_e32 v63, v26
	v_mov_b32_e32 v64, v26
	v_mov_b32_e32 v65, v26
	v_mov_b32_e32 v66, v26
	v_mov_b32_e32 v67, v26
	v_mov_b32_e32 v68, v26
	v_mov_b32_e32 v69, v26
	v_mov_b32_e32 v70, v26
	v_mov_b32_e32 v71, v26
	v_mov_b32_e32 v72, v26
	v_mov_b32_e32 v73, v26
	v_mov_b32_e32 v74, v26
	v_mov_b32_e32 v75, v26
	v_mov_b32_e32 v76, v26
	v_mov_b32_e32 v77, v26
	v_mov_b32_e32 v78, v26
	v_mov_b32_e32 v79, v26
	v_mov_b32_e32 v80, v26
	v_mov_b32_e32 v81, v26
	v_mov_b32_e32 v82, v26
	v_mov_b32_e32 v83, v26
	v_mov_b32_e32 v84, v26
	v_mov_b32_e32 v85, v26
	v_mov_b32_e32 v86, v26
	v_mov_b32_e32 v87, v26
	v_mov_b32_e32 v88, v26
	v_mov_b32_e32 v89, v26
	v_mov_b32_e32 v90, v26
	v_mov_b32_e32 v91, v26
	v_mov_b32_e32 v92, v26
	v_mov_b32_e32 v93, v26
	v_mov_b32_e32 v94, v26
	v_mov_b32_e32 v95, v26
	v_mov_b32_e32 v96, v26
	v_mov_b32_e32 v97, v26
	v_mov_b32_e32 v104, v26
	v_mov_b32_e32 v105, v26
	v_mov_b32_e32 v106, v26
	v_mov_b32_e32 v107, v26
	s_branch .LBB0_259
.LBB0_258:
	s_and_b32 s4, s17, 3
	s_mulk_i32 s4, 0x4800
	v_add_u32_e32 v98, s4, v131
	v_add_u32_e32 v165, v98, v127
	v_add3_u32 v168, v98, v128, v129
	ds_read_b128 v[98:101], v165
	ds_read_b128 v[108:111], v165 offset:512
	ds_read_b128 v[112:115], v165 offset:2304
	ds_read_b128 v[116:119], v165 offset:2816
	v_add_u32_e32 v195, 0x2000, v168
	v_add_u32_e32 v140, 0x2800, v168
	v_add_u32_e32 v144, 0x3000, v168
	v_add_u32_e32 v148, 0x3c00, v168
	ds_read2_b64 v[136:139], v195 offset0:128 offset1:160
	ds_read2_b64 v[140:143], v140 offset0:160 offset1:192
	ds_read2_b64 v[144:147], v144 offset0:192 offset1:224
	ds_read2_b64 v[148:151], v148 offset0:96 offset1:128
	s_add_i32 s4, s17, 2
	s_cmp_ge_u32 s4, s33
	s_cbranch_scc1 .Latto_nodma
	s_cmp_lt_u32 s4, s18
	s_cselect_b64 s[40:41], -1, 0
	s_and_b64 s[46:47], s[40:41], exec
	s_cselect_b32 s5, 0, s18
	s_sub_i32 s12, s17, s5
	s_add_i32 s12, s12, 2
	s_and_b64 s[46:47], s[40:41], exec
	s_cselect_b32 s20, s19, s10
	s_mul_hi_u32 s29, s12, 0x38000
	s_mul_i32 s12, s12, 0x38000
	s_cselect_b32 s13, s22, s28
	s_add_u32 s46, s20, s12
	s_addc_u32 s47, s13, s29
	s_and_b64 s[40:41], s[40:41], exec
	s_cselect_b32 s12, s26, s31
	s_cselect_b32 s13, s11, s30
	s_lshl_b32 s5, s5, 6
	s_sub_i32 s20, s39, s5
	s_lshl_b64 s[40:41], s[20:21], 1
	s_add_u32 s40, s13, s40
	s_addc_u32 s41, s12, s41
	s_and_b32 s4, s4, 3
	s_mulk_i32 s4, 0x4800
	s_add_i32 s4, s4, s80
	s_mov_b32 s5, m0
	s_mov_b32 m0, s4
	s_nop 0
	global_load_lds_dwordx4 v124, s[46:47]
	s_mov_b32 m0, s5
	s_addk_i32 s4, 0x2400
	s_mov_b32 s5, m0
	s_mov_b32 m0, s4
	s_nop 0
	global_load_lds_dwordx4 v125, s[40:41]
	s_mov_b32 m0, s5

; #define AT_WAIT_BAR(N) asm volatile("s_waitcnt vmcnt(" #N ") lgkmcnt(0)\n\ts_barrier" ::: "memory")
; DI void attn_odd_lds(Frame& F, const float* gk  , const float* gq  , bool with_ctx) {
;     ...
; #pragma unroll 1
;         for (int s = 0; s < n; ++s) {
;             if (s + 2 < n) AT_WAIT_BAR(4); else if (s + 1 < n) AT_WAIT_BAR(2); else AT_WAIT_BAR(0);
;             if (s + 3 < n) AT_ISSUE(s + 3);
.LBB0_259:
	s_bitcmp1_b32 s17, 0
	s_cbranch_scc1 .LBB0_258
	s_waitcnt vmcnt(0) lgkmcnt(0)
	s_barrier
	s_branch .LBB0_258
